# unit prologue: dropped two stale vmcnt(0) waits (they guarded the removed register-staged K/V loads) so Q loads overlap the first K/V LDS-DMA tiles
# baseline (speedup 1.0000x reference)
; #define LAS __attribute__((address_space(3)))
; __device__ __forceinline__ int opaque_tid() { int t = threadIdx.x; asm volatile("" : "+v"(t)); return t; }
; __device__ __forceinline__ int v_st_nat(int k, int c) { return ((k >> 3) * 2 + (c >> 5)) * 512 + ((k & 7) * 32 + (c & 31)) * 2; }
; __device__ __forceinline__ int v_rd_base(int lane) { return ((lane & 3) << 3) | (((lane >> 2) & 3) << 6) | (((lane >> 4) & 1) << 5) | (((lane >> 5) & 1) << 8); }
; #define AT_LOAD(K0, K1, V0, V1, T) do { const size_t e_ = (size_t)(128 * (T) + sr) * 64 + sc; \
;         K0 = *(const bf16x8*)(kcp + e_); V0 = *(const bf16x8*)(vcp + e_); K1 = *(const bf16x8*)(kcp + e_ + 64 * 64); V1 = *(const bf16x8*)(vcp + e_ + 64 * 64); } while (0)
; #define AT_STORE(K0, K1, V0, V1, BUF) do { *(LAS bf16x8*)(lds + AT_K + (BUF) * AT_KB + kst0) = K0; *(LAS bf16x8*)(lds + AT_K + (BUF) * AT_KB + kst1) = K1; \
;         *(LAS bf16x8*)(lds + AT_V + (BUF) * AT_VB + vst0) = V0; *(LAS bf16x8*)(lds + AT_V + (BUF) * AT_VB + vst1) = V1; } while (0)
; template <int VAR>
; __device__ __forceinline__ void attn_unit(const Args& a, int l, int b, int h, int qrow0  , bool ctxu, const bf16* Z, bf16* Y, LAS unsigned char* lds) {
;     const int tid = opaque_tid(), lane = tid & 63, wave = __builtin_amdgcn_readfirstlane(tid >> 6), r32 = lane & 31, hi = lane >> 5;
;     const int comp = wave >> 2, wq = wave & 3;
;     const int NT = ctxu ? 2 : 66;
;     const bf16* kcp = (const bf16*)(a.ws + WS_KC) + (size_t)(b * 4 + h) * 8448 * 64; const bf16* vcp = (const bf16*)(a.ws + WS_VC) + (size_t)(b * 4 + h) * 8448 * 64;
;     bf16x8 q0, q1;
;     { const bf16* qp = Z + (size_t)(qrow0 + wq * 32 + r32) * DIN + 512 + h * 64 + comp * 32 + hi * 8; q0 = *(const bf16x8*)(qp); q1 = *(const bf16x8*)(qp + 16); }
;     const int sr = tid >> 3, sc = (tid & 7) * 8;
;     const int kst0 = sr * 144 + sc * 2, kst1 = kst0 + 64 * 144, vst0 = v_st_nat(sr, sc), vst1 = v_st_nat(sr + 64, sc);
;     const int vb0 = (int)(unsigned)(uintptr_t)(lds + AT_V) + v_rd_base(lane);
;     LAS float* wsf = (LAS float*)(lds + AT_WS) + wave * 64;
;     f32x16 negm = f32x16{}, o0 = f32x16{}, o1 = f32x16{}, lacc = f32x16{};
;     float m = 0.f;
;     bf16x8 ka0, ka1, va0, va1, kb0, kb1, vb0_, vb1_;
;     ...
;     AT_LOAD(ka0, ka1, va0, va1, 0); AT_LOAD(kb0, kb1, vb0_, vb1_, 1); AT_STORE(ka0, ka1, va0, va1, 0);
.LBB0_429:
	s_ashr_i32 s9, s8, 6
	s_add_i32 s14, s9, s17
	s_lshl_b32 s9, s14, 11
	s_lshl_b32 s8, s8, 7
	v_mov_b32_e32 v12, v219
	s_and_b32 s9, s9, 0xffffe000
	s_and_b32 s8, s8, 0x1f80
	s_or_b32 s12, s8, s9
	v_readfirstlane_b32 s29, v12
	s_ashr_i32 s8, s29, 8
	s_bfe_u32 s9, s29, 0x20006
	s_mul_i32 s15, s14, 0x108000
	v_readlane_b32 s16, v254, 11
	v_ashrrev_i32_e32 v0, 3, v12
	v_lshlrev_b32_e32 v13, 3, v12
	s_mul_hi_i32 s13, s14, 0x108000
	s_add_u32 s36, s16, s15
	v_readlane_b32 s16, v254, 12
	v_and_b32_e32 v228, 56, v13
	v_ashrrev_i32_e32 v1, 31, v0
	s_addc_u32 s37, s16, s13
	v_readlane_b32 s16, v254, 13
	v_lshlrev_b32_e32 v2, 1, v228
	v_lshlrev_b64 v[4:5], 7, v[0:1]
	s_add_u32 s38, s16, s15
	v_readlane_b32 s15, v254, 14
	v_or_b32_e32 v6, v4, v2
	v_mov_b32_e32 v7, v5
	s_addc_u32 s39, s15, s13
	v_lshl_add_u64 v[8:9], s[36:37], 0, v[6:7]
	v_lshl_add_u64 v[10:11], s[38:39], 0, v[6:7]
	v_add_co_u32_e32 v8, vcc, s62, v8
	s_lshl_b32 s13, s9, 5
	s_nop 0
	v_addc_co_u32_e32 v9, vcc, 0, v9, vcc
	v_add_co_u32_e32 v8, vcc, s62, v10
	v_and_b32_e32 v247, 31, v12
	s_nop 0
	v_addc_co_u32_e32 v9, vcc, 0, v11, vcc
	s_or_b32 s60, s13, s12
	v_or_b32_e32 v1, s60, v247
	v_mov_b64_e32 v[8:9], s[0:1]
	v_mad_i64_i32 v[8:9], s[12:13], v1, s30, v[8:9]
	s_lshl_b32 s12, s14, 6
	s_and_b32 s28, s12, 0xc0
	s_lshl_b32 s72, s28, 1
	s_lshl_b32 s12, s8, 5
	v_bfe_u32 v248, v12, 5, 1
	v_lshl_add_u64 v[8:9], v[8:9], 0, s[72:73]
	s_ashr_i32 s13, s12, 31
	v_lshl_add_u64 v[8:9], s[12:13], 1, v[8:9]
	v_lshlrev_b32_e32 v216, 4, v248
	s_mov_b64 s[48:49], 0x4000
	v_lshl_add_u64 v[8:9], v[8:9], 0, v[216:217]
	v_lshl_add_u64 v[6:7], v[6:7], 0, s[48:49]
	global_load_dwordx4 v[136:139], v[8:9], off offset:1024
	global_load_dwordx4 v[140:143], v[8:9], off offset:1056
	s_mov_b32 s50, 0x1400000
	v_add_co_u32_e32 v8, vcc, s50, v8
	s_nop 1
	v_addc_co_u32_e32 v9, vcc, 0, v9, vcc
	global_load_dwordx4 v[150:153], v[8:9], off offset:1024
	global_load_dwordx4 v[154:157], v[8:9], off offset:1056
	v_lshl_add_u64 v[8:9], s[36:37], 0, v[6:7]
	v_lshl_add_u64 v[6:7], s[38:39], 0, v[6:7]
	v_add_co_u32_e32 v8, vcc, s62, v8
	s_movk_i32 s15, 0x90
	s_nop 0
	v_addc_co_u32_e32 v9, vcc, 0, v9, vcc
	v_add_co_u32_e32 v6, vcc, s62, v6
	v_mad_u64_u32 v[2:3], s[12:13], v0, s15, v[2:3]
	s_nop 0
	v_addc_co_u32_e32 v7, vcc, 0, v7, vcc
	v_lshlrev_b32_e32 v10, 5, v0
	v_and_b32_e32 v11, 24, v13
	s_movk_i32 s13, 0xe0
	v_add_u32_e32 v0, 64, v0
	v_lshrrev_b32_e32 v1, 5, v12
	v_bfe_u32 v3, v13, 5, 1
	s_mov_b32 s12, 0x7ffffe
	v_and_or_b32 v6, v10, s13, v11
	v_lshrrev_b32_e32 v0, 2, v0
	v_and_or_b32 v1, v1, s12, v3
	v_lshlrev_b32_e32 v6, 1, v6
	v_and_or_b32 v0, v0, s12, v3
	v_and_b32_e32 v227, 63, v12
	v_lshl_or_b32 v1, v1, 9, v6
	v_lshl_or_b32 v0, v0, 9, v6
	v_lshlrev_b32_e32 v6, 4, v12
	v_lshlrev_b32_e32 v3, 3, v227
	v_and_b32_e32 v6, 0xc0, v6
	v_lshlrev_b32_e32 v7, 1, v12
	v_and_or_b32 v6, v3, 24, v6
	v_and_b32_e32 v7, 32, v7
	v_and_b32_e32 v3, 0x100, v3
	v_or3_b32 v3, v6, v7, v3
	s_add_i32 s12, 0, 0x9000
	v_add_u32_e32 v249, s12, v3
	s_and_b32 s12, s29, 0x3fffffc0
	s_lshl_b32 s12, s12, 2
	s_add_i32 s31, s12, 0
	s_lshl_b32 s12, s8, 6
	s_add_i32 s12, s12, 0
	v_add_u32_e32 v229, 0, v0
	v_mov_b32_e32 v0, s12
	s_add_i32 s12, 0, 0xd000
	v_add_u32_e32 v251, 0, v1
	v_mad_u32_u24 v16, v247, s15, v0
	v_add_u32_e32 v233, s12, v3
	v_mad_i64_i32 v[0:1], s[12:13], s14, v246, v[4:5]
	v_add_u32_e32 v250, 0, v2
	v_and_b32_e32 v2, 7, v12
	v_readlane_b32 s12, v255, 17
	v_lshl_or_b32 v0, v2, 4, v0
	v_readlane_b32 s13, v255, 18
	v_mov_b32_e32 v14, v217
	v_mov_b32_e32 v15, v217
	s_add_i32 s31, s31, 0x11000
	v_lshl_add_u64 v[230:231], s[12:13], 0, v[0:1]
	v_mov_b32_e32 v0, v217
	v_mov_b32_e32 v1, v217
	v_mov_b32_e32 v2, v217
	v_mov_b32_e32 v3, v217
	v_mov_b32_e32 v4, v217
	v_mov_b32_e32 v5, v217
	v_mov_b32_e32 v6, v217
	v_mov_b32_e32 v7, v217
	v_mov_b32_e32 v8, v217
	v_mov_b32_e32 v9, v217
	v_mov_b32_e32 v10, v217
	v_mov_b32_e32 v11, v217
	v_mov_b32_e32 v12, v217
	v_mov_b32_e32 v13, v217
	v_mov_b32_e32 v234, 0
	v_add_u32_e32 v235, v16, v216
	v_mov_b64_e32 v[30:31], v[14:15]
	v_mov_b64_e32 v[46:47], v[14:15]
	v_cmp_gt_u32_e64 s[38:39], 32, v227
	v_lshl_add_u32 v232, v247, 2, s31
	s_mov_b64 s[36:37], 0
	s_mov_b32 s33, 0
	v_mov_b64_e32 v[28:29], v[12:13]
	v_mov_b64_e32 v[26:27], v[10:11]
	v_mov_b64_e32 v[24:25], v[8:9]
	v_mov_b64_e32 v[22:23], v[6:7]
	v_mov_b64_e32 v[20:21], v[4:5]
	v_mov_b64_e32 v[18:19], v[2:3]
	v_mov_b64_e32 v[16:17], v[0:1]
	v_mov_b64_e32 v[44:45], v[12:13]
	v_mov_b64_e32 v[42:43], v[10:11]
	v_mov_b64_e32 v[40:41], v[8:9]
	v_mov_b64_e32 v[38:39], v[6:7]
	v_mov_b64_e32 v[36:37], v[4:5]
	v_mov_b64_e32 v[34:35], v[2:3]
	v_mov_b64_e32 v[32:33], v[0:1]
	v_mov_b32_e32 v64, 0
	v_mov_b32_e32 v65, v234
	v_mov_b32_e32 v66, v234
	v_mov_b32_e32 v67, v234
	v_mov_b32_e32 v68, v234
	v_mov_b32_e32 v69, v234
	v_mov_b32_e32 v70, v234
	v_mov_b32_e32 v71, v234
	v_mov_b32_e32 v72, v234
	v_mov_b32_e32 v73, v234
	v_mov_b32_e32 v74, v234
	v_mov_b32_e32 v75, v234
	v_mov_b32_e32 v76, v234
	v_mov_b32_e32 v77, v234
	v_mov_b32_e32 v78, v234
	v_mov_b32_e32 v48, 0
	v_readlane_b32 s14, v255, 19
	v_readlane_b32 s15, v255, 20
	s_branch .LBB0_431
